# S5 pass 2 reuses the H tile left in LDS by pass 1 of the same item (no second staging)
# speedup vs baseline: 1.0692x; 1.0020x over previous
.LBB0_194:
	s_ashr_i32 s9, s8, 3
	s_and_b32 s4, s8, 7
	s_waitcnt vmcnt(0) lgkmcnt(0)
	s_barrier
	s_and_saveexec_b64 s[14:15], s[12:13]
	s_movk_i32 s5, 0x110
	s_movk_i32 s33, 0xdff
	s_branch .LBB0_197
